# t1 + in-proj generic tiles: wave owns 64 contiguous output columns (weight-row DMA permutation), epilogue stores 8 rows x 128 B full lines via private LDS transposition
# baseline (speedup 1.0000x reference)
.LBB0_209:
	s_andn2_b64 vcc, exec, s[2:3]
	s_cbranch_vccnz .LBB0_317
	v_lshrrev_b32_e32 v2, 1, v161
	v_lshrrev_b32_e32 v3, 5, v161
	v_and_b32_e32 v2, 24, v2
	v_and_b32_e32 v3, 4, v3
	v_bfe_u32 v4, v161, 2, 2
	v_lshlrev_b32_e32 v0, 4, v161
	v_and_b32_e32 v1, 32, v161
	v_bfe_u32 v10, v161, 2, 4
	v_or3_b32 v2, v3, v4, v2
	v_lshrrev_b32_e32 v3, 3, v161
	s_movk_i32 s1, 0x70
	v_bitop3_b32 v8, v0, v1, 48 bitop3:0x6c
	v_and_b32_e32 v9, 64, v161
	v_and_or_b32 v4, v3, s1, v10
	s_movk_i32 s1, 0x60
	v_add_u32_e32 v11, 0x2000, v0
	v_or_b32_e32 v1, v8, v9
	v_and_or_b32 v3, v3, s1, v2
	v_lshrrev_b32_e32 v0, 7, v11
	s_movk_i32 s1, 0xf0
	v_lshl_or_b32 v130, v3, 12, v1
	v_mov_b32_e32 v236, v130
	v_and_b32_e32 v238, 0x60000, v130
	v_add_u32_e32 v238, v238, v130
	v_mov_b32_e32 v130, v238
	v_and_or_b32 v3, v0, s1, v10
	s_movk_i32 s1, 0xe0
	v_and_or_b32 v0, v0, s1, v2
	s_lshr_b32 s10, s4, 6
	s_ashr_i32 s1, s0, 31
	s_ashr_i32 s7, s6, 31
	s_mov_b32 s87, s69
	s_lshr_b32 s5, s4, 8
	s_lshl_b32 s69, s10, 10
	s_lshl_b64 s[2:3], s[0:1], 20
	s_lshl_b64 s[8:9], s[6:7], 20
	s_add_u32 s8, s24, s8
	s_mov_b64 s[94:95], s[70:71]
	s_addc_u32 s9, s25, s9
	s_add_i32 s70, s69, 0
	v_writelane_b32 v247, s80, 28
	s_add_i32 m0, s70, 0x10000
	v_lshl_or_b32 v134, v0, 12, v1
	v_mov_b32_e32 v237, v134
	v_and_b32_e32 v239, 0x60000, v134
	v_add_u32_e32 v239, v239, v134
	v_mov_b32_e32 v134, v239
	v_writelane_b32 v247, s81, 29
	global_load_lds_dwordx4 v130, s[8:9]
	s_add_i32 m0, s70, 0x12000
	v_writelane_b32 v247, s78, 30
	s_add_u32 s36, s8, 0x20000
	global_load_lds_dwordx4 v134, s[8:9]
	v_writelane_b32 v247, s79, 31
	s_addc_u32 s37, s9, 0
	s_add_i32 m0, s70, 0x14000
	v_writelane_b32 v247, s75, 32
	global_load_lds_dwordx4 v130, s[36:37]
	s_add_i32 m0, s70, 0x16000
	v_lshl_or_b32 v128, v4, 12, v1
	global_load_lds_dwordx4 v134, s[36:37]
	v_readlane_b32 s36, v247, 16
	v_readlane_b32 s37, v247, 17
	s_add_u32 s2, s36, s2
	s_addc_u32 s3, s37, s3
	s_add_i32 s71, s70, 0x2000
	s_mov_b32 m0, s70
	s_add_u32 s36, s2, 0x80000
	s_mov_b64 s[96:97], s[72:73]
	v_lshl_or_b32 v132, v3, 12, v1
	global_load_lds_dwordx4 v128, s[2:3]
	s_mov_b32 m0, s71
	s_addc_u32 s37, s3, 0
	s_add_i32 s72, s70, 0x4000
	global_load_lds_dwordx4 v132, s[2:3]
	s_mov_b32 m0, s72
	s_add_i32 s73, s70, 0x6000
	global_load_lds_dwordx4 v128, s[36:37]
	s_mov_b32 m0, s73
	v_mov_b32_e32 v131, 0
	global_load_lds_dwordx4 v132, s[36:37]
	v_mov_b32_e32 v135, v131
	v_mov_b32_e32 v129, v131
	v_mov_b32_e32 v133, v131
	s_cmp_eq_u32 s5, 1
	s_mov_b32 s98, s74
	s_mov_b32 s86, s65
	s_mov_b32 s37, 0
	v_lshl_add_u64 v[6:7], s[8:9], 0, v[130:131]
	v_lshl_add_u64 v[4:5], s[8:9], 0, v[134:135]
	v_lshl_add_u64 v[0:1], s[2:3], 0, v[128:129]
	s_cselect_b64 s[38:39], -1, 0
	s_cmp_lg_u32 s5, 1
	v_lshl_add_u64 v[2:3], s[2:3], 0, v[132:133]
	s_cbranch_scc1 .LBB0_212
	s_barrier
.LBB0_212:
	s_mov_b64 s[40:41], 0x80
	s_and_b32 s1, s10, 3
	s_add_i32 m0, s70, 0x18000
	v_lshl_add_u64 v[6:7], v[6:7], 0, s[40:41]
	s_ashr_i32 s74, s92, 31
	s_mov_b32 s99, s76
	s_ashr_i32 s75, s76, 31
	s_lshl_b32 s7, s5, 13
	s_lshl_b32 s33, s1, 12
	s_waitcnt vmcnt(2)
	s_barrier
	global_load_lds_dwordx4 v[6:7], off
	v_lshl_add_u64 v[4:5], v[4:5], 0, s[40:41]
	s_add_i32 m0, s70, 0x1a000
	s_add_i32 s76, s70, 0x8000
	s_add_i32 s77, s70, 0xa000
	global_load_lds_dwordx4 v[4:5], off
	v_lshl_add_u64 v[0:1], v[0:1], 0, s[40:41]
	s_mov_b32 m0, s76
	s_add_u32 s10, s8, 0x20080
	global_load_lds_dwordx4 v[0:1], off
	v_lshl_add_u64 v[0:1], v[2:3], 0, s[40:41]
	s_mov_b32 m0, s77
	s_addc_u32 s11, s9, 0
	global_load_lds_dwordx4 v[0:1], off
	s_add_i32 m0, s70, 0x1c000
	v_lshl_add_u64 v[0:1], s[10:11], 0, v[130:131]
	global_load_lds_dwordx4 v[0:1], off
	v_lshl_add_u64 v[0:1], s[10:11], 0, v[134:135]
	s_add_i32 m0, s70, 0x1e000
	v_bfe_u32 v2, v161, 4, 2
	global_load_lds_dwordx4 v[0:1], off
	v_lshlrev_b32_e32 v0, 4, v2
	v_lshlrev_b32_e32 v3, 6, v161
	s_movk_i32 s10, 0x3c0
	v_and_b32_e32 v1, 15, v161
	v_and_or_b32 v5, v3, s10, v0
	v_lshlrev_b32_e32 v3, 2, v161
	v_lshlrev_b32_e32 v4, 3, v2
	v_and_b32_e32 v6, 32, v3
	v_cmp_eq_u32_e64 s[10:11], 0, v2
	v_lshlrev_b32_e32 v2, 5, v2
	v_mov_b32_e32 v3, v131
	v_lshl_or_b32 v186, s5, 6, v1
	v_lshl_or_b32 v1, v1, 6, v0
	v_lshl_add_u64 v[136:137], s[26:27], 0, v[2:3]
	v_lshl_add_u64 v[138:139], s[28:29], 0, v[2:3]
	v_bitop3_b32 v2, v1, s7, v6 bitop3:0xde
	v_mov_b32_e32 v1, v131
	v_lshl_add_u64 v[140:141], s[82:83], 0, v[0:1]
	v_lshlrev_b32_e32 v0, 9, v161
	v_and_b32_e32 v0, 0x70000, v0
	v_lshlrev_b32_e32 v1, 12, v10
	v_or3_b32 v0, v8, v0, v1
	s_cmpk_lt_u32 s4, 0x100
	v_add_u32_e32 v142, v0, v9
	v_lshlrev_b32_e32 v0, 5, v11
	s_cselect_b64 s[42:43], -1, 0
	s_cmp_lg_u32 s1, 0
	v_and_b32_e32 v0, 0xf0000, v0
	s_waitcnt vmcnt(6)
	s_cselect_b64 s[44:45], -1, 0
	s_cmp_eq_u32 s1, 1
	v_or3_b32 v0, v8, v0, v1
	v_bitop3_b32 v187, s33, v5, v6 bitop3:0xf6
	s_cselect_b64 s[4:5], -1, 0
	v_add_u32_e32 v144, v0, v9
	s_add_i32 s79, 0, 0x10000
	s_add_i32 s80, 0, 0x14000
	v_mbcnt_lo_u32_b32 v0, -1, 0
	s_mov_b32 s78, s92
	v_lshl_or_b32 v188, s1, 5, v4
	v_lshl_or_b32 v242, s1, 6, v4
	s_mov_b32 s101, 0x20000
	s_and_b64 s[46:47], s[10:11], s[4:5]
	v_mov_b32_e32 v143, v131
	v_mov_b32_e32 v145, v131
	v_mov_b64_e32 v[146:147], 0x680
	v_mov_b64_e32 v[148:149], 0x67f
	v_add_u32_e32 v189, s79, v187
	v_add_u32_e32 v190, s80, v187
	v_add_u32_e32 v191, 0, v2
	s_lshl_b32 s81, s1, 2
	s_movk_i32 s82, 0xc00
	v_mbcnt_hi_u32_b32 v192, -1, v0
	v_lshrrev_b32_e32 v253, 6, v161
	v_lshlrev_b32_e32 v253, 12, v253
	v_add_u32_e32 v253, 0x20000, v253
	v_and_b32_e32 v234, 15, v192
	v_mul_u32_u24_e32 v234, 0x90, v234
	v_lshrrev_b32_e32 v235, 4, v192
	v_lshl_add_u32 v234, v235, 4, v234
	v_add_u32_e32 v234, v234, v253
	v_lshrrev_b32_e32 v235, 3, v192
	v_lshlrev_b32_e32 v240, 2, v235
	v_add_u32_e32 v241, 32, v240
	v_mul_u32_u24_e32 v235, 0x90, v235
	v_and_b32_e32 v252, 7, v192
	v_lshlrev_b32_e32 v252, 4, v252
	v_add3_u32 v235, v235, v252, v253
	v_mov_b32_e32 v253, 0
	s_mov_b32 s83, 0
	s_barrier
	s_branch .LBB0_215

.LBB0_218:
	s_waitcnt lgkmcnt(0)
	ds_read_b128 v[150:153], v189
	ds_read_b128 v[154:157], v189 offset:1024
	ds_read_b128 v[162:165], v189 offset:2048
	ds_read_b128 v[166:169], v189 offset:3072
	ds_read_b128 v[170:173], v190
	ds_read_b128 v[174:177], v190 offset:1024
	ds_read_b128 v[178:181], v190 offset:2048
	ds_read_b128 v[182:185], v190 offset:3072
	s_add_u32 s8, s2, 0xfff80080
	s_addc_u32 s9, s3, -1
	s_cmp_eq_u32 s58, 28
	s_cselect_b32 s57, s1, s9
	s_cselect_b32 s56, s7, s8
	s_cselect_b32 s9, s33, s51
	s_cselect_b32 s8, s36, s49
	s_cbranch_scc0 .Lwm_keep
	s_cmp_eq_u32 s48, 25
	s_cbranch_scc1 .Lwm_norm
	s_mov_b32 s101, 0x20000
	v_mov_b32_e32 v130, v238
	v_mov_b32_e32 v134, v239
	s_branch .Lwm_keep
.Lwm_norm:
	s_mov_b32 s101, 0x80000
	v_mov_b32_e32 v130, v236
	v_mov_b32_e32 v134, v237
.Lwm_keep:
	v_lshl_add_u64 v[158:159], s[2:3], 0, v[142:143]
	s_add_i32 m0, s70, 0xc000
	ds_read_b128 v[194:197], v191
	ds_read_b128 v[198:201], v191 offset:1024
	ds_read_b128 v[202:205], v191 offset:2048
	ds_read_b128 v[206:209], v191 offset:3072
	ds_read_b128 v[210:213], v191 offset:4096
	ds_read_b128 v[214:217], v191 offset:5120
	ds_read_b128 v[218:221], v191 offset:6144
	ds_read_b128 v[222:225], v191 offset:7168
	global_load_lds_dwordx4 v[158:159], off
	v_lshl_add_u64 v[158:159], s[2:3], 0, v[144:145]
	s_add_i32 m0, s70, 0xe000
	s_nop 0
	global_load_lds_dwordx4 v[158:159], off
	s_waitcnt vmcnt(8)
	s_waitcnt lgkmcnt(0)
	s_barrier
	s_setprio 1
	s_waitcnt lgkmcnt(0)
	v_mfma_f32_16x16x32_bf16 v[124:127], v[150:153], v[194:197], v[124:127]
	v_mfma_f32_16x16x32_bf16 v[120:123], v[162:165], v[194:197], v[120:123]
	v_mfma_f32_16x16x32_bf16 v[108:111], v[150:153], v[202:205], v[108:111]
	v_mfma_f32_16x16x32_bf16 v[104:107], v[162:165], v[202:205], v[104:107]
	v_mfma_f32_16x16x32_bf16 v[92:95], v[150:153], v[210:213], v[92:95]
	v_mfma_f32_16x16x32_bf16 v[88:91], v[162:165], v[210:213], v[88:91]
	v_mfma_f32_16x16x32_bf16 v[76:79], v[150:153], v[218:221], v[76:79]
	v_mfma_f32_16x16x32_bf16 v[72:75], v[162:165], v[218:221], v[72:75]
	v_mfma_f32_16x16x32_bf16 v[124:127], v[154:157], v[198:201], v[124:127]
	v_mfma_f32_16x16x32_bf16 v[120:123], v[166:169], v[198:201], v[120:123]
	v_mfma_f32_16x16x32_bf16 v[108:111], v[154:157], v[206:209], v[108:111]
	v_mfma_f32_16x16x32_bf16 v[104:107], v[166:169], v[206:209], v[104:107]
	v_mfma_f32_16x16x32_bf16 v[92:95], v[154:157], v[214:217], v[92:95]
	v_mfma_f32_16x16x32_bf16 v[88:91], v[166:169], v[214:217], v[88:91]
	v_mfma_f32_16x16x32_bf16 v[76:79], v[154:157], v[222:225], v[76:79]
	v_mfma_f32_16x16x32_bf16 v[72:75], v[166:169], v[222:225], v[72:75]
	s_setprio 0
	s_setprio 1
	v_mfma_f32_16x16x32_bf16 v[116:119], v[170:173], v[194:197], v[116:119]
	v_mfma_f32_16x16x32_bf16 v[112:115], v[178:181], v[194:197], v[112:115]
	v_mfma_f32_16x16x32_bf16 v[100:103], v[170:173], v[202:205], v[100:103]
	v_mfma_f32_16x16x32_bf16 v[96:99], v[178:181], v[202:205], v[96:99]
	v_mfma_f32_16x16x32_bf16 v[84:87], v[170:173], v[210:213], v[84:87]
	v_mfma_f32_16x16x32_bf16 v[80:83], v[178:181], v[210:213], v[80:83]
	v_mfma_f32_16x16x32_bf16 v[68:71], v[170:173], v[218:221], v[68:71]
	v_mfma_f32_16x16x32_bf16 v[64:67], v[178:181], v[218:221], v[64:67]
	v_mfma_f32_16x16x32_bf16 v[116:119], v[174:177], v[198:201], v[116:119]
	v_mfma_f32_16x16x32_bf16 v[112:115], v[182:185], v[198:201], v[112:115]
	v_mfma_f32_16x16x32_bf16 v[100:103], v[174:177], v[206:209], v[100:103]
	v_mfma_f32_16x16x32_bf16 v[96:99], v[182:185], v[206:209], v[96:99]
	v_mfma_f32_16x16x32_bf16 v[84:87], v[174:177], v[214:217], v[84:87]
	v_mfma_f32_16x16x32_bf16 v[80:83], v[182:185], v[214:217], v[80:83]
	v_mfma_f32_16x16x32_bf16 v[68:71], v[174:177], v[222:225], v[68:71]
	v_mfma_f32_16x16x32_bf16 v[64:67], v[182:185], v[222:225], v[64:67]
	s_setprio 0
	s_barrier
	s_add_i32 s59, s79, s69
	v_lshl_add_u64 v[158:159], s[8:9], 0, v[130:131]
	s_mov_b32 m0, s59
	ds_read_b128 v[194:197], v191 offset:16384
	ds_read_b128 v[198:201], v191 offset:17408
	ds_read_b128 v[202:205], v191 offset:18432
	ds_read_b128 v[206:209], v191 offset:19456
	ds_read_b128 v[210:213], v191 offset:20480
	ds_read_b128 v[214:217], v191 offset:21504
	ds_read_b128 v[218:221], v191 offset:22528
	ds_read_b128 v[222:225], v191 offset:23552
	global_load_lds_dwordx4 v[158:159], off
	s_add_i32 m0, s59, 0x2000
	s_add_u32 s60, s8, s101
	v_lshl_add_u64 v[226:227], s[8:9], 0, v[134:135]
	s_addc_u32 s61, s9, 0
	s_add_i32 s59, s80, s69
	global_load_lds_dwordx4 v[226:227], off
	v_lshl_add_u64 v[228:229], s[60:61], 0, v[130:131]
	s_mov_b32 m0, s59
	v_lshl_add_u64 v[230:231], s[56:57], 0, v[132:133]
	global_load_lds_dwordx4 v[228:229], off
	v_lshl_add_u64 v[228:229], s[60:61], 0, v[134:135]
	s_add_i32 m0, s59, 0x2000
	s_nop 0
	global_load_lds_dwordx4 v[228:229], off
	v_lshl_add_u64 v[228:229], s[56:57], 0, v[128:129]
	s_mov_b32 m0, s70
	s_nop 0
	global_load_lds_dwordx4 v[228:229], off
	s_mov_b32 m0, s71
	s_nop 0
	global_load_lds_dwordx4 v[230:231], off
	s_waitcnt vmcnt(8)
	s_waitcnt lgkmcnt(0)
	s_barrier
	s_setprio 1
	s_waitcnt lgkmcnt(0)
	v_mfma_f32_16x16x32_bf16 v[60:63], v[150:153], v[194:197], v[60:63]
	v_mfma_f32_16x16x32_bf16 v[56:59], v[162:165], v[194:197], v[56:59]
	v_mfma_f32_16x16x32_bf16 v[44:47], v[150:153], v[202:205], v[44:47]
	v_mfma_f32_16x16x32_bf16 v[40:43], v[162:165], v[202:205], v[40:43]
	v_mfma_f32_16x16x32_bf16 v[28:31], v[150:153], v[210:213], v[28:31]
	v_mfma_f32_16x16x32_bf16 v[24:27], v[162:165], v[210:213], v[24:27]
	v_mfma_f32_16x16x32_bf16 v[12:15], v[150:153], v[218:221], v[12:15]
	v_mfma_f32_16x16x32_bf16 v[8:11], v[162:165], v[218:221], v[8:11]
	v_mfma_f32_16x16x32_bf16 v[60:63], v[154:157], v[198:201], v[60:63]
	v_mfma_f32_16x16x32_bf16 v[56:59], v[166:169], v[198:201], v[56:59]
	v_mfma_f32_16x16x32_bf16 v[44:47], v[154:157], v[206:209], v[44:47]
	v_mfma_f32_16x16x32_bf16 v[40:43], v[166:169], v[206:209], v[40:43]
	v_mfma_f32_16x16x32_bf16 v[28:31], v[154:157], v[214:217], v[28:31]
	v_mfma_f32_16x16x32_bf16 v[24:27], v[166:169], v[214:217], v[24:27]
	v_mfma_f32_16x16x32_bf16 v[12:15], v[154:157], v[222:225], v[12:15]
	v_mfma_f32_16x16x32_bf16 v[8:11], v[166:169], v[222:225], v[8:11]
	s_setprio 0
	s_setprio 1
	v_mfma_f32_16x16x32_bf16 v[52:55], v[170:173], v[194:197], v[52:55]
	v_mfma_f32_16x16x32_bf16 v[48:51], v[178:181], v[194:197], v[48:51]
	v_mfma_f32_16x16x32_bf16 v[36:39], v[170:173], v[202:205], v[36:39]
	v_mfma_f32_16x16x32_bf16 v[32:35], v[178:181], v[202:205], v[32:35]
	v_mfma_f32_16x16x32_bf16 v[20:23], v[170:173], v[210:213], v[20:23]
	v_mfma_f32_16x16x32_bf16 v[16:19], v[178:181], v[210:213], v[16:19]
	v_mfma_f32_16x16x32_bf16 v[4:7], v[170:173], v[218:221], v[4:7]
	v_mfma_f32_16x16x32_bf16 v[0:3], v[178:181], v[218:221], v[0:3]
	v_mfma_f32_16x16x32_bf16 v[52:55], v[174:177], v[198:201], v[52:55]
	v_mfma_f32_16x16x32_bf16 v[48:51], v[182:185], v[198:201], v[48:51]
	v_mfma_f32_16x16x32_bf16 v[36:39], v[174:177], v[206:209], v[36:39]
	v_mfma_f32_16x16x32_bf16 v[32:35], v[182:185], v[206:209], v[32:35]
	v_mfma_f32_16x16x32_bf16 v[20:23], v[174:177], v[214:217], v[20:23]
	v_mfma_f32_16x16x32_bf16 v[16:19], v[182:185], v[214:217], v[16:19]
	v_mfma_f32_16x16x32_bf16 v[4:7], v[174:177], v[222:225], v[4:7]
	v_mfma_f32_16x16x32_bf16 v[0:3], v[182:185], v[222:225], v[0:3]
	s_setprio 0
	s_barrier
	s_add_i32 s59, 0, 0x18000
	s_add_i32 s60, 0, 0x1c000
	v_add_u32_e32 v166, s59, v187
	v_add_u32_e32 v182, s60, v187
	ds_read_b128 v[150:153], v166
	ds_read_b128 v[154:157], v166 offset:1024
	ds_read_b128 v[162:165], v166 offset:2048
	ds_read_b128 v[166:169], v166 offset:3072
	ds_read_b128 v[170:173], v182
	ds_read_b128 v[174:177], v182 offset:1024
	ds_read_b128 v[178:181], v182 offset:2048
	ds_read_b128 v[182:185], v182 offset:3072
	s_add_u32 s56, s56, 0x80000
	s_addc_u32 s57, s57, 0
	s_mov_b32 m0, s72
	v_lshl_add_u64 v[232:233], s[56:57], 0, v[128:129]
	ds_read_b128 v[194:197], v191 offset:32768
	ds_read_b128 v[198:201], v191 offset:33792
	ds_read_b128 v[202:205], v191 offset:34816
	ds_read_b128 v[206:209], v191 offset:35840
	ds_read_b128 v[210:213], v191 offset:36864
	ds_read_b128 v[214:217], v191 offset:37888
	ds_read_b128 v[218:221], v191 offset:38912
	ds_read_b128 v[222:225], v191 offset:39936
	global_load_lds_dwordx4 v[232:233], off
	v_lshl_add_u64 v[232:233], s[56:57], 0, v[132:133]
	s_mov_b32 m0, s73
	s_nop 0
	global_load_lds_dwordx4 v[232:233], off
	s_waitcnt vmcnt(8)
	s_waitcnt lgkmcnt(0)
	s_barrier
	s_setprio 1
	s_waitcnt lgkmcnt(0)
	v_mfma_f32_16x16x32_bf16 v[124:127], v[150:153], v[194:197], v[124:127]
	v_mfma_f32_16x16x32_bf16 v[120:123], v[162:165], v[194:197], v[120:123]
	v_mfma_f32_16x16x32_bf16 v[108:111], v[150:153], v[202:205], v[108:111]
	v_mfma_f32_16x16x32_bf16 v[104:107], v[162:165], v[202:205], v[104:107]
	v_mfma_f32_16x16x32_bf16 v[92:95], v[150:153], v[210:213], v[92:95]
	v_mfma_f32_16x16x32_bf16 v[88:91], v[162:165], v[210:213], v[88:91]
	v_mfma_f32_16x16x32_bf16 v[76:79], v[150:153], v[218:221], v[76:79]
	v_mfma_f32_16x16x32_bf16 v[72:75], v[162:165], v[218:221], v[72:75]
	v_mfma_f32_16x16x32_bf16 v[124:127], v[154:157], v[198:201], v[124:127]
	v_mfma_f32_16x16x32_bf16 v[120:123], v[166:169], v[198:201], v[120:123]
	v_mfma_f32_16x16x32_bf16 v[108:111], v[154:157], v[206:209], v[108:111]
	v_mfma_f32_16x16x32_bf16 v[104:107], v[166:169], v[206:209], v[104:107]
	v_mfma_f32_16x16x32_bf16 v[92:95], v[154:157], v[214:217], v[92:95]
	v_mfma_f32_16x16x32_bf16 v[88:91], v[166:169], v[214:217], v[88:91]
	v_mfma_f32_16x16x32_bf16 v[76:79], v[154:157], v[222:225], v[76:79]
	v_mfma_f32_16x16x32_bf16 v[72:75], v[166:169], v[222:225], v[72:75]
	s_setprio 0
	s_setprio 1
	v_mfma_f32_16x16x32_bf16 v[116:119], v[170:173], v[194:197], v[116:119]
	v_mfma_f32_16x16x32_bf16 v[112:115], v[178:181], v[194:197], v[112:115]
	v_mfma_f32_16x16x32_bf16 v[100:103], v[170:173], v[202:205], v[100:103]
	v_mfma_f32_16x16x32_bf16 v[96:99], v[178:181], v[202:205], v[96:99]
	v_mfma_f32_16x16x32_bf16 v[84:87], v[170:173], v[210:213], v[84:87]
	v_mfma_f32_16x16x32_bf16 v[80:83], v[178:181], v[210:213], v[80:83]
	v_mfma_f32_16x16x32_bf16 v[68:71], v[170:173], v[218:221], v[68:71]
	v_mfma_f32_16x16x32_bf16 v[64:67], v[178:181], v[218:221], v[64:67]
	v_mfma_f32_16x16x32_bf16 v[116:119], v[174:177], v[198:201], v[116:119]
	v_mfma_f32_16x16x32_bf16 v[112:115], v[182:185], v[198:201], v[112:115]
	v_mfma_f32_16x16x32_bf16 v[100:103], v[174:177], v[206:209], v[100:103]
	v_mfma_f32_16x16x32_bf16 v[96:99], v[182:185], v[206:209], v[96:99]
	v_mfma_f32_16x16x32_bf16 v[84:87], v[174:177], v[214:217], v[84:87]
	v_mfma_f32_16x16x32_bf16 v[80:83], v[182:185], v[214:217], v[80:83]
	v_mfma_f32_16x16x32_bf16 v[68:71], v[174:177], v[222:225], v[68:71]
	v_mfma_f32_16x16x32_bf16 v[64:67], v[182:185], v[222:225], v[64:67]
	s_setprio 0
	s_barrier
	s_add_i32 s56, s59, s69
	v_lshl_add_u64 v[158:159], v[158:159], 0, s[40:41]
	s_mov_b32 m0, s56
	ds_read_b128 v[194:197], v191 offset:49152
	ds_read_b128 v[198:201], v191 offset:50176
	ds_read_b128 v[202:205], v191 offset:51200
	ds_read_b128 v[206:209], v191 offset:52224
	ds_read_b128 v[210:213], v191 offset:53248
	ds_read_b128 v[214:217], v191 offset:54272
	ds_read_b128 v[218:221], v191 offset:55296
	ds_read_b128 v[222:225], v191 offset:56320
	global_load_lds_dwordx4 v[158:159], off
	s_add_i32 m0, s56, 0x2000
	s_add_u32 s8, s8, s101
	v_lshl_add_u64 v[158:159], v[226:227], 0, s[40:41]
	s_addc_u32 s9, s9, 0
	s_add_u32 s8, s8, 0x80
	s_addc_u32 s9, s9, 0
	s_add_i32 s56, s60, s69
	global_load_lds_dwordx4 v[158:159], off
	v_lshl_add_u64 v[158:159], s[8:9], 0, v[130:131]
	s_mov_b32 m0, s56
	s_nop 0
	global_load_lds_dwordx4 v[158:159], off
	v_lshl_add_u64 v[158:159], s[8:9], 0, v[134:135]
	s_add_i32 m0, s56, 0x2000
	s_nop 0
	global_load_lds_dwordx4 v[158:159], off
	v_lshl_add_u64 v[158:159], v[228:229], 0, s[40:41]
	s_mov_b32 m0, s76
	s_nop 0
	global_load_lds_dwordx4 v[158:159], off
	v_lshl_add_u64 v[158:159], v[230:231], 0, s[40:41]
	s_mov_b32 m0, s77
	s_nop 0
	global_load_lds_dwordx4 v[158:159], off
	s_waitcnt vmcnt(8)
	s_waitcnt lgkmcnt(0)
	s_barrier
	s_setprio 1
	s_waitcnt lgkmcnt(0)
	v_mfma_f32_16x16x32_bf16 v[60:63], v[150:153], v[194:197], v[60:63]
	v_mfma_f32_16x16x32_bf16 v[56:59], v[162:165], v[194:197], v[56:59]
	v_mfma_f32_16x16x32_bf16 v[44:47], v[150:153], v[202:205], v[44:47]
	v_mfma_f32_16x16x32_bf16 v[40:43], v[162:165], v[202:205], v[40:43]
	v_mfma_f32_16x16x32_bf16 v[28:31], v[150:153], v[210:213], v[28:31]
	v_mfma_f32_16x16x32_bf16 v[24:27], v[162:165], v[210:213], v[24:27]
	v_mfma_f32_16x16x32_bf16 v[12:15], v[150:153], v[218:221], v[12:15]
	v_mfma_f32_16x16x32_bf16 v[8:11], v[162:165], v[218:221], v[8:11]
	v_mfma_f32_16x16x32_bf16 v[60:63], v[154:157], v[198:201], v[60:63]
	v_mfma_f32_16x16x32_bf16 v[56:59], v[166:169], v[198:201], v[56:59]
	v_mfma_f32_16x16x32_bf16 v[44:47], v[154:157], v[206:209], v[44:47]
	v_mfma_f32_16x16x32_bf16 v[40:43], v[166:169], v[206:209], v[40:43]
	v_mfma_f32_16x16x32_bf16 v[28:31], v[154:157], v[214:217], v[28:31]
	v_mfma_f32_16x16x32_bf16 v[24:27], v[166:169], v[214:217], v[24:27]
	v_mfma_f32_16x16x32_bf16 v[12:15], v[154:157], v[222:225], v[12:15]
	v_mfma_f32_16x16x32_bf16 v[8:11], v[166:169], v[222:225], v[8:11]
	s_setprio 0
	s_setprio 1
	v_mfma_f32_16x16x32_bf16 v[52:55], v[170:173], v[194:197], v[52:55]
	v_mfma_f32_16x16x32_bf16 v[48:51], v[178:181], v[194:197], v[48:51]
	v_mfma_f32_16x16x32_bf16 v[36:39], v[170:173], v[202:205], v[36:39]
	v_mfma_f32_16x16x32_bf16 v[32:35], v[178:181], v[202:205], v[32:35]
	v_mfma_f32_16x16x32_bf16 v[20:23], v[170:173], v[210:213], v[20:23]
	v_mfma_f32_16x16x32_bf16 v[16:19], v[178:181], v[210:213], v[16:19]
	v_mfma_f32_16x16x32_bf16 v[4:7], v[170:173], v[218:221], v[4:7]
	v_mfma_f32_16x16x32_bf16 v[0:3], v[178:181], v[218:221], v[0:3]
	v_mfma_f32_16x16x32_bf16 v[52:55], v[174:177], v[198:201], v[52:55]
	v_mfma_f32_16x16x32_bf16 v[48:51], v[182:185], v[198:201], v[48:51]
	v_mfma_f32_16x16x32_bf16 v[36:39], v[174:177], v[206:209], v[36:39]
	v_mfma_f32_16x16x32_bf16 v[32:35], v[182:185], v[206:209], v[32:35]
	v_mfma_f32_16x16x32_bf16 v[20:23], v[174:177], v[214:217], v[20:23]
	v_mfma_f32_16x16x32_bf16 v[16:19], v[182:185], v[214:217], v[16:19]
	v_mfma_f32_16x16x32_bf16 v[4:7], v[174:177], v[222:225], v[4:7]
	v_mfma_f32_16x16x32_bf16 v[0:3], v[182:185], v[222:225], v[0:3]
	s_setprio 0
	s_barrier
	s_add_i32 s58, s58, 2
	s_add_u32 s2, s2, 0x100
	s_addc_u32 s3, s3, 0
	s_add_u32 s49, s49, 0x100
	s_addc_u32 s51, s51, 0
	s_cmp_gt_u32 s58, 29
	s_cbranch_scc0 .LBB0_218
	s_and_b64 vcc, exec, s[42:43]
	s_cbranch_vccz .LBB0_222
	s_barrier
	v_lshl_add_u32 v150, s0, 8, v186
	s_cmp_lg_u32 s6, 25
	s_mov_b64 s[0:1], -1
	s_cbranch_scc1 .LBB0_223

.LBB0_243:
	v_add_u32_e32 v152, s33, v242
	v_ashrrev_i32_e32 v153, 31, v152
	v_lshl_add_u64 v[152:153], v[152:153], 1, s[58:59]
	v_mul_lo_u32 v178, s3, v150
	v_mul_lo_u32 v179, s2, v151
	v_mad_u64_u32 v[174:175], s[58:59], s2, v150, 0
	v_add3_u32 v175, v175, v179, v178
	v_lshl_add_u64 v[174:175], v[174:175], 1, v[152:153]
	v_cvt_pk_bf16_f32 v166, v166, v167
	v_cvt_pk_bf16_f32 v167, v172, v173
	v_mov_b32_e32 v171, v170
	v_cvt_pk_bf16_f32 v168, v168, v169
	v_cvt_pk_bf16_f32 v169, v176, v177
	ds_write_b128 v234, v[166:169]
	v_pk_mul_f32 v[172:173], v[116:117], v[170:171]
	s_and_b64 vcc, exec, s[6:7]
	v_mov_b32_e32 v166, v170
	v_mov_b32_e32 v167, v170
	v_pk_mul_f32 v[168:169], v[118:119], v[166:167]
	v_pk_mul_f32 v[166:167], v[114:115], v[166:167]
	v_pk_mul_f32 v[170:171], v[112:113], v[170:171]
	v_mov_b32_e32 v176, v172
	v_mov_b32_e32 v177, v173
	v_mov_b32_e32 v180, v168
	v_mov_b32_e32 v181, v169
	v_mov_b32_e32 v178, v170
	v_mov_b32_e32 v179, v171
	v_mov_b32_e32 v182, v166
	v_mov_b32_e32 v183, v167
	s_cbranch_vccnz .LBB0_245
	v_mul_f32_e32 v177, 0xbfb8aa3b, v170
	v_mul_f32_e32 v178, 0xbfb8aa3b, v173
	v_exp_f32_e32 v177, v177
	v_exp_f32_e32 v179, v178
	v_mul_f32_e32 v178, 0xbfb8aa3b, v171
	v_exp_f32_e32 v180, v178
	v_add_f32_e32 v177, 1.0, v177
	v_mul_f32_e32 v181, 0xbfb8aa3b, v166
	v_mul_f32_e32 v182, 0xbfb8aa3b, v169
	v_mul_f32_e32 v176, 0xbfb8aa3b, v172
	v_rcp_f32_e32 v178, v177
	v_add_f32_e32 v177, 1.0, v179
	v_add_f32_e32 v179, 1.0, v180
	v_mul_f32_e32 v180, 0xbfb8aa3b, v168
	v_exp_f32_e32 v181, v181
	v_exp_f32_e32 v183, v182
	v_mul_f32_e32 v182, 0xbfb8aa3b, v167
	v_exp_f32_e32 v176, v176
	v_exp_f32_e32 v180, v180
	v_exp_f32_e32 v184, v182
	v_add_f32_e32 v181, 1.0, v181
	v_add_f32_e32 v176, 1.0, v176
	v_add_f32_e32 v180, 1.0, v180
	v_rcp_f32_e32 v182, v181
	v_add_f32_e32 v181, 1.0, v183
	v_add_f32_e32 v183, 1.0, v184
	v_rcp_f32_e32 v176, v176
	v_rcp_f32_e32 v177, v177
	v_rcp_f32_e32 v179, v179
	v_rcp_f32_e32 v180, v180
	v_rcp_f32_e32 v181, v181
	v_rcp_f32_e32 v183, v183
	v_pk_mul_f32 v[176:177], v[172:173], v[176:177]
	v_pk_mul_f32 v[178:179], v[170:171], v[178:179]
	v_pk_mul_f32 v[180:181], v[168:169], v[180:181]
	v_pk_mul_f32 v[182:183], v[166:167], v[182:183]
.LBB0_245:
	s_cmp_lg_u64 s[62:63], 0
	s_cselect_b64 s[60:61], -1, 0
	s_ashr_i32 s9, s8, 31
	s_lshl_b64 s[8:9], s[8:9], 2
	s_add_u32 s8, s62, s8
	s_addc_u32 s9, s63, s9
	s_add_u32 s58, s8, s81
	s_addc_u32 s59, s9, 0
	s_cmp_eq_u64 s[62:63], 0
	v_cvt_pk_bf16_f32 v176, v176, v177
	v_cvt_pk_bf16_f32 v177, v180, v181
	v_cvt_pk_bf16_f32 v178, v178, v179
	v_cvt_pk_bf16_f32 v179, v182, v183
	ds_write_b128 v234, v[176:179] offset:64
	ds_bpermute_b32 v248, v240, v174
	ds_bpermute_b32 v249, v240, v175
	ds_bpermute_b32 v250, v241, v174
	ds_bpermute_b32 v251, v241, v175
	ds_read_b128 v[226:229], v235
	ds_read_b128 v[230:233], v235 offset:1152
	s_waitcnt lgkmcnt(0)
	v_lshl_add_u64 v[248:249], v[248:249], 0, v[252:253]
	v_lshl_add_u64 v[250:251], v[250:251], 0, v[252:253]
	global_store_dwordx4 v[248:249], v[226:229], off
	global_store_dwordx4 v[250:251], v[230:233], off
	s_cbranch_scc1 .LBB0_249
	v_mul_f32_e32 v165, v165, v165
	v_mul_f32_e32 v163, v163, v163
	v_fmac_f32_e32 v165, v164, v164
	v_fmac_f32_e32 v163, v162, v162
	v_mul_f32_e32 v159, v159, v159
	v_add_f32_e32 v162, v165, v163
	v_fmac_f32_e32 v159, v158, v158
	v_mul_f32_e32 v157, v157, v157
	v_add_f32_e32 v158, v159, v162
	v_fmac_f32_e32 v157, v156, v156
	v_add_f32_e32 v156, v157, v158
	v_mul_f32_e32 v157, v173, v173
	v_mul_f32_e32 v158, v169, v169
	v_fmac_f32_e32 v157, v172, v172
	v_fmac_f32_e32 v158, v168, v168
	v_add_f32_e32 v157, v157, v158
	v_mul_f32_e32 v158, v171, v171
	v_fmac_f32_e32 v158, v170, v170
	v_add_f32_e32 v157, v158, v157
	v_mul_f32_e32 v158, v167, v167
	v_fmac_f32_e32 v158, v166, v166
	v_add_f32_e32 v157, v158, v157
	v_and_b32_e32 v158, 64, v192
	v_add_f32_e32 v156, v156, v157
	v_xor_b32_e32 v157, 16, v192
	v_add_u32_e32 v158, 64, v158
	v_cmp_lt_i32_e32 vcc, v157, v158
	s_nop 1
	v_cndmask_b32_e32 v157, v192, v157, vcc
	v_lshlrev_b32_e32 v157, 2, v157
	ds_bpermute_b32 v157, v157, v156
	s_waitcnt lgkmcnt(0)
	v_add_f32_e32 v156, v156, v157
	v_xor_b32_e32 v157, 32, v192
	v_cmp_lt_i32_e32 vcc, v157, v158
	s_nop 1
	v_cndmask_b32_e32 v157, v192, v157, vcc
	v_lshlrev_b32_e32 v157, 2, v157
	ds_bpermute_b32 v157, v157, v156
	s_and_saveexec_b64 s[8:9], s[10:11]
	s_cbranch_execz .LBB0_248
	s_waitcnt lgkmcnt(0)
	v_add_f32_e32 v158, v156, v157
	v_mul_lo_u32 v159, s1, v150
	v_mul_lo_u32 v151, s0, v151
	v_mad_u64_u32 v[156:157], s[62:63], s0, v150, 0
	v_add3_u32 v157, v157, v151, v159
	v_lshl_add_u64 v[156:157], v[156:157], 2, s[58:59]
	global_store_dword v[156:157], v158, off

.LBB0_251:
	v_or_b32_e32 v166, 16, v150
	v_ashrrev_i32_e32 v151, 31, v166
	v_mul_lo_u32 v167, s2, v151
	v_mul_lo_u32 v180, s3, v166
	v_mad_u64_u32 v[176:177], s[8:9], s2, v166, 0
	v_add3_u32 v177, v177, v167, v180
	v_lshl_add_u64 v[176:177], v[176:177], 1, v[152:153]
	v_cvt_pk_bf16_f32 v168, v168, v169
	v_cvt_pk_bf16_f32 v169, v174, v175
	v_mov_b32_e32 v173, v172
	v_cvt_pk_bf16_f32 v170, v170, v171
	v_cvt_pk_bf16_f32 v171, v178, v179
	ds_write_b128 v234, v[168:171]
	v_pk_mul_f32 v[174:175], v[100:101], v[172:173]
	s_and_b64 vcc, exec, s[6:7]
	v_mov_b32_e32 v168, v172
	v_mov_b32_e32 v169, v172
	v_pk_mul_f32 v[170:171], v[102:103], v[168:169]
	v_pk_mul_f32 v[168:169], v[98:99], v[168:169]
	v_pk_mul_f32 v[172:173], v[96:97], v[172:173]
	v_mov_b32_e32 v178, v174
	v_mov_b32_e32 v179, v175
	v_mov_b32_e32 v182, v170
	v_mov_b32_e32 v183, v171
	v_mov_b32_e32 v180, v172
	v_mov_b32_e32 v181, v173
	v_mov_b32_e32 v184, v168
	v_mov_b32_e32 v185, v169
	s_cbranch_vccnz .LBB0_253
	v_mul_f32_e32 v167, 0xbfb8aa3b, v174
	v_exp_f32_e32 v167, v167
	v_mul_f32_e32 v178, 0xbfb8aa3b, v172
	v_exp_f32_e32 v178, v178
	v_mul_f32_e32 v180, 0xbfb8aa3b, v173
	v_add_f32_e32 v167, 1.0, v167
	v_exp_f32_e32 v181, v180
	v_add_f32_e32 v179, 1.0, v178
	v_rcp_f32_e32 v178, v167
	v_mul_f32_e32 v167, 0xbfb8aa3b, v175
	v_exp_f32_e32 v167, v167
	v_rcp_f32_e32 v180, v179
	v_mul_f32_e32 v184, 0xbfb8aa3b, v169
	v_exp_f32_e32 v185, v184
	v_add_f32_e32 v167, 1.0, v167
	v_rcp_f32_e32 v179, v167
	v_add_f32_e32 v167, 1.0, v181
	v_mul_f32_e32 v181, 0xbfb8aa3b, v170
	v_exp_f32_e32 v182, v181
	v_mul_f32_e32 v181, 0xbfb8aa3b, v168
	v_exp_f32_e32 v183, v181
	v_rcp_f32_e32 v181, v167
	v_add_f32_e32 v167, 1.0, v182
	v_rcp_f32_e32 v182, v167
	v_add_f32_e32 v167, 1.0, v183
	v_mul_f32_e32 v183, 0xbfb8aa3b, v171
	v_exp_f32_e32 v183, v183
	v_rcp_f32_e32 v184, v167
	v_pk_mul_f32 v[178:179], v[174:175], v[178:179]
	v_pk_mul_f32 v[180:181], v[172:173], v[180:181]
	v_add_f32_e32 v167, 1.0, v183
	v_rcp_f32_e32 v183, v167
	v_add_f32_e32 v167, 1.0, v185
	v_rcp_f32_e32 v185, v167
	v_pk_mul_f32 v[182:183], v[170:171], v[182:183]
	v_pk_mul_f32 v[184:185], v[168:169], v[184:185]
.LBB0_253:
	v_cndmask_b32_e64 v167, 0, 1, s[60:61]
	v_cmp_ne_u32_e64 s[8:9], 1, v167
	s_andn2_b64 vcc, exec, s[60:61]
	v_cvt_pk_bf16_f32 v178, v178, v179
	v_cvt_pk_bf16_f32 v179, v182, v183
	v_cvt_pk_bf16_f32 v180, v180, v181
	v_cvt_pk_bf16_f32 v181, v184, v185
	ds_write_b128 v234, v[178:181] offset:64
	ds_bpermute_b32 v248, v240, v176
	ds_bpermute_b32 v249, v240, v177
	ds_bpermute_b32 v250, v241, v176
	ds_bpermute_b32 v251, v241, v177
	ds_read_b128 v[226:229], v235
	ds_read_b128 v[230:233], v235 offset:1152
	s_waitcnt lgkmcnt(0)
	v_lshl_add_u64 v[248:249], v[248:249], 0, v[252:253]
	v_lshl_add_u64 v[250:251], v[250:251], 0, v[252:253]
	global_store_dwordx4 v[248:249], v[226:229], off
	global_store_dwordx4 v[250:251], v[230:233], off
	s_cbranch_vccnz .LBB0_257
	v_mul_f32_e32 v165, v165, v165
	v_mul_f32_e32 v163, v163, v163
	v_fmac_f32_e32 v165, v164, v164
	v_fmac_f32_e32 v163, v162, v162
	v_mul_f32_e32 v159, v159, v159
	v_add_f32_e32 v162, v165, v163
	v_fmac_f32_e32 v159, v158, v158
	v_mul_f32_e32 v157, v157, v157
	v_add_f32_e32 v158, v159, v162
	v_fmac_f32_e32 v157, v156, v156
	v_add_f32_e32 v156, v157, v158
	v_mul_f32_e32 v157, v175, v175
	v_mul_f32_e32 v158, v171, v171
	v_fmac_f32_e32 v157, v174, v174
	v_fmac_f32_e32 v158, v170, v170
	v_add_f32_e32 v157, v157, v158
	v_mul_f32_e32 v158, v173, v173
	v_fmac_f32_e32 v158, v172, v172
	v_add_f32_e32 v157, v158, v157
	v_mul_f32_e32 v158, v169, v169
	v_fmac_f32_e32 v158, v168, v168
	v_add_f32_e32 v157, v158, v157
	v_and_b32_e32 v158, 64, v192
	v_add_f32_e32 v156, v156, v157
	v_xor_b32_e32 v157, 16, v192
	v_add_u32_e32 v158, 64, v158
	v_cmp_lt_i32_e32 vcc, v157, v158
	s_nop 1
	v_cndmask_b32_e32 v157, v192, v157, vcc
	v_lshlrev_b32_e32 v157, 2, v157
	ds_bpermute_b32 v157, v157, v156
	s_waitcnt lgkmcnt(0)
	v_add_f32_e32 v156, v156, v157
	v_xor_b32_e32 v157, 32, v192
	v_cmp_lt_i32_e32 vcc, v157, v158
	s_nop 1
	v_cndmask_b32_e32 v157, v192, v157, vcc
	v_lshlrev_b32_e32 v157, 2, v157
	ds_bpermute_b32 v157, v157, v156
	s_and_saveexec_b64 s[60:61], s[10:11]
	s_cbranch_execz .LBB0_256
	s_waitcnt lgkmcnt(0)
	v_add_f32_e32 v158, v156, v157
	v_mul_lo_u32 v159, s1, v166
	v_mul_lo_u32 v151, s0, v151
	v_mad_u64_u32 v[156:157], s[62:63], s0, v166, 0
	v_add3_u32 v157, v157, v151, v159
	v_lshl_add_u64 v[156:157], v[156:157], 2, s[58:59]
	global_store_dword v[156:157], v158, off

.LBB0_259:
	v_or_b32_e32 v166, 32, v150
	v_ashrrev_i32_e32 v151, 31, v166
	v_mul_lo_u32 v167, s2, v151
	v_mul_lo_u32 v180, s3, v166
	v_mad_u64_u32 v[176:177], s[60:61], s2, v166, 0
	v_add3_u32 v177, v177, v167, v180
	v_lshl_add_u64 v[176:177], v[176:177], 1, v[152:153]
	v_cvt_pk_bf16_f32 v168, v168, v169
	v_cvt_pk_bf16_f32 v169, v174, v175
	v_mov_b32_e32 v173, v172
	v_cvt_pk_bf16_f32 v170, v170, v171
	v_cvt_pk_bf16_f32 v171, v178, v179
	ds_write_b128 v234, v[168:171]
	v_pk_mul_f32 v[174:175], v[84:85], v[172:173]
	s_and_b64 vcc, exec, s[6:7]
	v_mov_b32_e32 v168, v172
	v_mov_b32_e32 v169, v172
	v_pk_mul_f32 v[170:171], v[86:87], v[168:169]
	v_pk_mul_f32 v[168:169], v[82:83], v[168:169]
	v_pk_mul_f32 v[172:173], v[80:81], v[172:173]
	v_mov_b32_e32 v178, v174
	v_mov_b32_e32 v179, v175
	v_mov_b32_e32 v182, v170
	v_mov_b32_e32 v183, v171
	v_mov_b32_e32 v180, v172
	v_mov_b32_e32 v181, v173
	v_mov_b32_e32 v184, v168
	v_mov_b32_e32 v185, v169
	s_cbranch_vccnz .LBB0_261
	v_mul_f32_e32 v167, 0xbfb8aa3b, v174
	v_exp_f32_e32 v167, v167
	v_mul_f32_e32 v178, 0xbfb8aa3b, v172
	v_exp_f32_e32 v178, v178
	v_mul_f32_e32 v180, 0xbfb8aa3b, v173
	v_add_f32_e32 v167, 1.0, v167
	v_exp_f32_e32 v181, v180
	v_add_f32_e32 v179, 1.0, v178
	v_rcp_f32_e32 v178, v167
	v_mul_f32_e32 v167, 0xbfb8aa3b, v175
	v_exp_f32_e32 v167, v167
	v_rcp_f32_e32 v180, v179
	v_mul_f32_e32 v184, 0xbfb8aa3b, v169
	v_exp_f32_e32 v185, v184
	v_add_f32_e32 v167, 1.0, v167
	v_rcp_f32_e32 v179, v167
	v_add_f32_e32 v167, 1.0, v181
	v_mul_f32_e32 v181, 0xbfb8aa3b, v170
	v_exp_f32_e32 v182, v181
	v_mul_f32_e32 v181, 0xbfb8aa3b, v168
	v_exp_f32_e32 v183, v181
	v_rcp_f32_e32 v181, v167
	v_add_f32_e32 v167, 1.0, v182
	v_rcp_f32_e32 v182, v167
	v_add_f32_e32 v167, 1.0, v183
	v_mul_f32_e32 v183, 0xbfb8aa3b, v171
	v_exp_f32_e32 v183, v183
	v_rcp_f32_e32 v184, v167
	v_pk_mul_f32 v[178:179], v[174:175], v[178:179]
	v_pk_mul_f32 v[180:181], v[172:173], v[180:181]
	v_add_f32_e32 v167, 1.0, v183
	v_rcp_f32_e32 v183, v167
	v_add_f32_e32 v167, 1.0, v185
	v_rcp_f32_e32 v185, v167
	v_pk_mul_f32 v[182:183], v[170:171], v[182:183]
	v_pk_mul_f32 v[184:185], v[168:169], v[184:185]
.LBB0_261:
	s_and_b64 vcc, exec, s[8:9]
	v_cvt_pk_bf16_f32 v178, v178, v179
	v_cvt_pk_bf16_f32 v179, v182, v183
	v_cvt_pk_bf16_f32 v180, v180, v181
	v_cvt_pk_bf16_f32 v181, v184, v185
	ds_write_b128 v234, v[178:181] offset:64
	ds_bpermute_b32 v248, v240, v176
	ds_bpermute_b32 v249, v240, v177
	ds_bpermute_b32 v250, v241, v176
	ds_bpermute_b32 v251, v241, v177
	ds_read_b128 v[226:229], v235
	ds_read_b128 v[230:233], v235 offset:1152
	s_waitcnt lgkmcnt(0)
	v_lshl_add_u64 v[248:249], v[248:249], 0, v[252:253]
	v_lshl_add_u64 v[250:251], v[250:251], 0, v[252:253]
	global_store_dwordx4 v[248:249], v[226:229], off
	global_store_dwordx4 v[250:251], v[230:233], off
	s_cbranch_vccnz .LBB0_265
	v_mul_f32_e32 v165, v165, v165
	v_mul_f32_e32 v163, v163, v163
	v_fmac_f32_e32 v165, v164, v164
	v_fmac_f32_e32 v163, v162, v162
	v_mul_f32_e32 v159, v159, v159
	v_add_f32_e32 v162, v165, v163
	v_fmac_f32_e32 v159, v158, v158
	v_mul_f32_e32 v157, v157, v157
	v_add_f32_e32 v158, v159, v162
	v_fmac_f32_e32 v157, v156, v156
	v_add_f32_e32 v156, v157, v158
	v_mul_f32_e32 v157, v175, v175
	v_mul_f32_e32 v158, v171, v171
	v_fmac_f32_e32 v157, v174, v174
	v_fmac_f32_e32 v158, v170, v170
	v_add_f32_e32 v157, v157, v158
	v_mul_f32_e32 v158, v173, v173
	v_fmac_f32_e32 v158, v172, v172
	v_add_f32_e32 v157, v158, v157
	v_mul_f32_e32 v158, v169, v169
	v_fmac_f32_e32 v158, v168, v168
	v_add_f32_e32 v157, v158, v157
	v_and_b32_e32 v158, 64, v192
	v_add_f32_e32 v156, v156, v157
	v_xor_b32_e32 v157, 16, v192
	v_add_u32_e32 v158, 64, v158
	v_cmp_lt_i32_e32 vcc, v157, v158
	s_nop 1
	v_cndmask_b32_e32 v157, v192, v157, vcc
	v_lshlrev_b32_e32 v157, 2, v157
	ds_bpermute_b32 v157, v157, v156
	s_waitcnt lgkmcnt(0)
	v_add_f32_e32 v156, v156, v157
	v_xor_b32_e32 v157, 32, v192
	v_cmp_lt_i32_e32 vcc, v157, v158
	s_nop 1
	v_cndmask_b32_e32 v157, v192, v157, vcc
	v_lshlrev_b32_e32 v157, 2, v157
	ds_bpermute_b32 v157, v157, v156
	s_and_saveexec_b64 s[60:61], s[10:11]
	s_cbranch_execz .LBB0_264
	s_waitcnt lgkmcnt(0)
	v_add_f32_e32 v158, v156, v157
	v_mul_lo_u32 v159, s1, v166
	v_mul_lo_u32 v151, s0, v151
	v_mad_u64_u32 v[156:157], s[62:63], s0, v166, 0
	v_add3_u32 v157, v157, v151, v159
	v_lshl_add_u64 v[156:157], v[156:157], 2, s[58:59]
	global_store_dword v[156:157], v158, off

.LBB0_267:
	v_or_b32_e32 v166, 48, v150
	v_ashrrev_i32_e32 v151, 31, v166
	v_mul_lo_u32 v167, s2, v151
	v_mul_lo_u32 v180, s3, v166
	v_mad_u64_u32 v[176:177], s[60:61], s2, v166, 0
	v_add3_u32 v177, v177, v167, v180
	v_lshl_add_u64 v[176:177], v[176:177], 1, v[152:153]
	v_cvt_pk_bf16_f32 v168, v168, v169
	v_cvt_pk_bf16_f32 v169, v174, v175
	v_mov_b32_e32 v173, v172
	v_cvt_pk_bf16_f32 v170, v170, v171
	v_cvt_pk_bf16_f32 v171, v178, v179
	ds_write_b128 v234, v[168:171]
	v_pk_mul_f32 v[174:175], v[68:69], v[172:173]
	s_and_b64 vcc, exec, s[6:7]
	v_mov_b32_e32 v168, v172
	v_mov_b32_e32 v169, v172
	v_pk_mul_f32 v[170:171], v[70:71], v[168:169]
	v_pk_mul_f32 v[168:169], v[66:67], v[168:169]
	v_pk_mul_f32 v[172:173], v[64:65], v[172:173]
	v_mov_b32_e32 v178, v174
	v_mov_b32_e32 v179, v175
	v_mov_b32_e32 v182, v170
	v_mov_b32_e32 v183, v171
	v_mov_b32_e32 v180, v172
	v_mov_b32_e32 v181, v173
	v_mov_b32_e32 v184, v168
	v_mov_b32_e32 v185, v169
	s_cbranch_vccnz .LBB0_269
	v_mul_f32_e32 v167, 0xbfb8aa3b, v174
	v_exp_f32_e32 v167, v167
	v_mul_f32_e32 v178, 0xbfb8aa3b, v172
	v_exp_f32_e32 v178, v178
	v_mul_f32_e32 v180, 0xbfb8aa3b, v173
	v_add_f32_e32 v167, 1.0, v167
	v_exp_f32_e32 v181, v180
	v_add_f32_e32 v179, 1.0, v178
	v_rcp_f32_e32 v178, v167
	v_mul_f32_e32 v167, 0xbfb8aa3b, v175
	v_exp_f32_e32 v167, v167
	v_rcp_f32_e32 v180, v179
	v_mul_f32_e32 v184, 0xbfb8aa3b, v169
	v_exp_f32_e32 v185, v184
	v_add_f32_e32 v167, 1.0, v167
	v_rcp_f32_e32 v179, v167
	v_add_f32_e32 v167, 1.0, v181
	v_mul_f32_e32 v181, 0xbfb8aa3b, v170
	v_exp_f32_e32 v182, v181
	v_mul_f32_e32 v181, 0xbfb8aa3b, v168
	v_exp_f32_e32 v183, v181
	v_rcp_f32_e32 v181, v167
	v_add_f32_e32 v167, 1.0, v182
	v_rcp_f32_e32 v182, v167
	v_add_f32_e32 v167, 1.0, v183
	v_mul_f32_e32 v183, 0xbfb8aa3b, v171
	v_exp_f32_e32 v183, v183
	v_rcp_f32_e32 v184, v167
	v_pk_mul_f32 v[178:179], v[174:175], v[178:179]
	v_pk_mul_f32 v[180:181], v[172:173], v[180:181]
	v_add_f32_e32 v167, 1.0, v183
	v_rcp_f32_e32 v183, v167
	v_add_f32_e32 v167, 1.0, v185
	v_rcp_f32_e32 v185, v167
	v_pk_mul_f32 v[182:183], v[170:171], v[182:183]
	v_pk_mul_f32 v[184:185], v[168:169], v[184:185]

.LBB0_275:
	v_add_u32_e32 v166, 0x80, v150
	v_ashrrev_i32_e32 v151, 31, v166
	v_mul_lo_u32 v167, s2, v151
	v_mul_lo_u32 v180, s3, v166
	v_mad_u64_u32 v[176:177], s[60:61], s2, v166, 0
	v_add3_u32 v177, v177, v167, v180
	v_lshl_add_u64 v[176:177], v[176:177], 1, v[152:153]
	v_cvt_pk_bf16_f32 v168, v168, v169
	v_cvt_pk_bf16_f32 v169, v174, v175
	v_mov_b32_e32 v173, v172
	v_cvt_pk_bf16_f32 v170, v170, v171
	v_cvt_pk_bf16_f32 v171, v178, v179
	ds_write_b128 v234, v[168:171]
	v_pk_mul_f32 v[174:175], v[52:53], v[172:173]
	s_and_b64 vcc, exec, s[6:7]
	v_mov_b32_e32 v168, v172
	v_mov_b32_e32 v169, v172
	v_pk_mul_f32 v[170:171], v[54:55], v[168:169]
	v_pk_mul_f32 v[168:169], v[50:51], v[168:169]
	v_pk_mul_f32 v[172:173], v[48:49], v[172:173]
	v_mov_b32_e32 v178, v174
	v_mov_b32_e32 v179, v175
	v_mov_b32_e32 v182, v170
	v_mov_b32_e32 v183, v171
	v_mov_b32_e32 v180, v172
	v_mov_b32_e32 v181, v173
	v_mov_b32_e32 v184, v168
	v_mov_b32_e32 v185, v169
	s_cbranch_vccnz .LBB0_277
	v_mul_f32_e32 v167, 0xbfb8aa3b, v174
	v_exp_f32_e32 v167, v167
	v_mul_f32_e32 v178, 0xbfb8aa3b, v172
	v_exp_f32_e32 v178, v178
	v_mul_f32_e32 v180, 0xbfb8aa3b, v173
	v_add_f32_e32 v167, 1.0, v167
	v_exp_f32_e32 v181, v180
	v_add_f32_e32 v179, 1.0, v178
	v_rcp_f32_e32 v178, v167
	v_mul_f32_e32 v167, 0xbfb8aa3b, v175
	v_exp_f32_e32 v167, v167
	v_rcp_f32_e32 v180, v179
	v_mul_f32_e32 v184, 0xbfb8aa3b, v169
	v_exp_f32_e32 v185, v184
	v_add_f32_e32 v167, 1.0, v167
	v_rcp_f32_e32 v179, v167
	v_add_f32_e32 v167, 1.0, v181
	v_mul_f32_e32 v181, 0xbfb8aa3b, v170
	v_exp_f32_e32 v182, v181
	v_mul_f32_e32 v181, 0xbfb8aa3b, v168
	v_exp_f32_e32 v183, v181
	v_rcp_f32_e32 v181, v167
	v_add_f32_e32 v167, 1.0, v182
	v_rcp_f32_e32 v182, v167
	v_add_f32_e32 v167, 1.0, v183
	v_mul_f32_e32 v183, 0xbfb8aa3b, v171
	v_exp_f32_e32 v183, v183
	v_rcp_f32_e32 v184, v167
	v_pk_mul_f32 v[178:179], v[174:175], v[178:179]
	v_pk_mul_f32 v[180:181], v[172:173], v[180:181]
	v_add_f32_e32 v167, 1.0, v183
	v_rcp_f32_e32 v183, v167
	v_add_f32_e32 v167, 1.0, v185
	v_rcp_f32_e32 v185, v167
	v_pk_mul_f32 v[182:183], v[170:171], v[182:183]
	v_pk_mul_f32 v[184:185], v[168:169], v[184:185]

.LBB0_283:
	v_add_u32_e32 v166, 0x90, v150
	v_ashrrev_i32_e32 v151, 31, v166
	v_mul_lo_u32 v167, s2, v151
	v_mul_lo_u32 v180, s3, v166
	v_mad_u64_u32 v[176:177], s[60:61], s2, v166, 0
	v_add3_u32 v177, v177, v167, v180
	v_lshl_add_u64 v[176:177], v[176:177], 1, v[152:153]
	v_cvt_pk_bf16_f32 v168, v168, v169
	v_cvt_pk_bf16_f32 v169, v174, v175
	v_mov_b32_e32 v173, v172
	v_cvt_pk_bf16_f32 v170, v170, v171
	v_cvt_pk_bf16_f32 v171, v178, v179
	ds_write_b128 v234, v[168:171]
	v_pk_mul_f32 v[174:175], v[36:37], v[172:173]
	s_and_b64 vcc, exec, s[6:7]
	v_mov_b32_e32 v168, v172
	v_mov_b32_e32 v169, v172
	v_pk_mul_f32 v[170:171], v[38:39], v[168:169]
	v_pk_mul_f32 v[168:169], v[34:35], v[168:169]
	v_pk_mul_f32 v[172:173], v[32:33], v[172:173]
	v_mov_b32_e32 v178, v174
	v_mov_b32_e32 v179, v175
	v_mov_b32_e32 v182, v170
	v_mov_b32_e32 v183, v171
	v_mov_b32_e32 v180, v172
	v_mov_b32_e32 v181, v173
	v_mov_b32_e32 v184, v168
	v_mov_b32_e32 v185, v169
	s_cbranch_vccnz .LBB0_285
	v_mul_f32_e32 v167, 0xbfb8aa3b, v174
	v_exp_f32_e32 v167, v167
	v_mul_f32_e32 v178, 0xbfb8aa3b, v172
	v_exp_f32_e32 v178, v178
	v_mul_f32_e32 v180, 0xbfb8aa3b, v173
	v_add_f32_e32 v167, 1.0, v167
	v_exp_f32_e32 v181, v180
	v_add_f32_e32 v179, 1.0, v178
	v_rcp_f32_e32 v178, v167
	v_mul_f32_e32 v167, 0xbfb8aa3b, v175
	v_exp_f32_e32 v167, v167
	v_rcp_f32_e32 v180, v179
	v_mul_f32_e32 v184, 0xbfb8aa3b, v169
	v_exp_f32_e32 v185, v184
	v_add_f32_e32 v167, 1.0, v167
	v_rcp_f32_e32 v179, v167
	v_add_f32_e32 v167, 1.0, v181
	v_mul_f32_e32 v181, 0xbfb8aa3b, v170
	v_exp_f32_e32 v182, v181
	v_mul_f32_e32 v181, 0xbfb8aa3b, v168
	v_exp_f32_e32 v183, v181
	v_rcp_f32_e32 v181, v167
	v_add_f32_e32 v167, 1.0, v182
	v_rcp_f32_e32 v182, v167
	v_add_f32_e32 v167, 1.0, v183
	v_mul_f32_e32 v183, 0xbfb8aa3b, v171
	v_exp_f32_e32 v183, v183
	v_rcp_f32_e32 v184, v167
	v_pk_mul_f32 v[178:179], v[174:175], v[178:179]
	v_pk_mul_f32 v[180:181], v[172:173], v[180:181]
	v_add_f32_e32 v167, 1.0, v183
	v_rcp_f32_e32 v183, v167
	v_add_f32_e32 v167, 1.0, v185
	v_rcp_f32_e32 v185, v167
	v_pk_mul_f32 v[182:183], v[170:171], v[182:183]
	v_pk_mul_f32 v[184:185], v[168:169], v[184:185]

.LBB0_291:
	v_add_u32_e32 v166, 0xa0, v150
	v_ashrrev_i32_e32 v151, 31, v166
	v_mul_lo_u32 v167, s2, v151
	v_mul_lo_u32 v180, s3, v166
	v_mad_u64_u32 v[176:177], s[60:61], s2, v166, 0
	v_add3_u32 v177, v177, v167, v180
	v_lshl_add_u64 v[176:177], v[176:177], 1, v[152:153]
	v_cvt_pk_bf16_f32 v168, v168, v169
	v_cvt_pk_bf16_f32 v169, v174, v175
	v_mov_b32_e32 v173, v172
	v_cvt_pk_bf16_f32 v170, v170, v171
	v_cvt_pk_bf16_f32 v171, v178, v179
	ds_write_b128 v234, v[168:171]
	v_pk_mul_f32 v[174:175], v[20:21], v[172:173]
	s_and_b64 vcc, exec, s[6:7]
	v_mov_b32_e32 v168, v172
	v_mov_b32_e32 v169, v172
	v_pk_mul_f32 v[170:171], v[22:23], v[168:169]
	v_pk_mul_f32 v[168:169], v[18:19], v[168:169]
	v_pk_mul_f32 v[172:173], v[16:17], v[172:173]
	v_mov_b32_e32 v178, v174
	v_mov_b32_e32 v179, v175
	v_mov_b32_e32 v182, v170
	v_mov_b32_e32 v183, v171
	v_mov_b32_e32 v180, v172
	v_mov_b32_e32 v181, v173
	v_mov_b32_e32 v184, v168
	v_mov_b32_e32 v185, v169
	s_cbranch_vccnz .LBB0_293
	v_mul_f32_e32 v167, 0xbfb8aa3b, v174
	v_exp_f32_e32 v167, v167
	v_mul_f32_e32 v178, 0xbfb8aa3b, v172
	v_exp_f32_e32 v178, v178
	v_mul_f32_e32 v180, 0xbfb8aa3b, v173
	v_add_f32_e32 v167, 1.0, v167
	v_exp_f32_e32 v181, v180
	v_add_f32_e32 v179, 1.0, v178
	v_rcp_f32_e32 v178, v167
	v_mul_f32_e32 v167, 0xbfb8aa3b, v175
	v_exp_f32_e32 v167, v167
	v_rcp_f32_e32 v180, v179
	v_mul_f32_e32 v184, 0xbfb8aa3b, v169
	v_exp_f32_e32 v185, v184
	v_add_f32_e32 v167, 1.0, v167
	v_rcp_f32_e32 v179, v167
	v_add_f32_e32 v167, 1.0, v181
	v_mul_f32_e32 v181, 0xbfb8aa3b, v170
	v_exp_f32_e32 v182, v181
	v_mul_f32_e32 v181, 0xbfb8aa3b, v168
	v_exp_f32_e32 v183, v181
	v_rcp_f32_e32 v181, v167
	v_add_f32_e32 v167, 1.0, v182
	v_rcp_f32_e32 v182, v167
	v_add_f32_e32 v167, 1.0, v183
	v_mul_f32_e32 v183, 0xbfb8aa3b, v171
	v_exp_f32_e32 v183, v183
	v_rcp_f32_e32 v184, v167
	v_pk_mul_f32 v[178:179], v[174:175], v[178:179]
	v_pk_mul_f32 v[180:181], v[172:173], v[180:181]
	v_add_f32_e32 v167, 1.0, v183
	v_rcp_f32_e32 v183, v167
	v_add_f32_e32 v167, 1.0, v185
	v_rcp_f32_e32 v185, v167
	v_pk_mul_f32 v[182:183], v[170:171], v[182:183]
	v_pk_mul_f32 v[184:185], v[168:169], v[184:185]

.LBB0_299:
	v_add_u32_e32 v164, 0xb0, v150
	v_ashrrev_i32_e32 v151, 31, v164
	v_mul_lo_u32 v165, s2, v151
	v_mul_lo_u32 v178, s3, v164
	v_mad_u64_u32 v[172:173], s[2:3], s2, v164, 0
	v_add3_u32 v173, v173, v165, v178
	v_mov_b32_e32 v169, v168
	v_lshl_add_u64 v[172:173], v[172:173], 1, v[152:153]
	v_mov_b32_e32 v152, v168
	v_mov_b32_e32 v153, v168
	v_cvt_pk_bf16_f32 v178, v166, v167
	v_cvt_pk_bf16_f32 v179, v174, v175
	v_cvt_pk_bf16_f32 v180, v170, v171
	v_cvt_pk_bf16_f32 v181, v176, v177
	v_pk_mul_f32 v[166:167], v[6:7], v[152:153]
	v_pk_mul_f32 v[170:171], v[4:5], v[168:169]
	v_pk_mul_f32 v[152:153], v[2:3], v[152:153]
	v_pk_mul_f32 v[168:169], v[0:1], v[168:169]
	ds_write_b128 v234, v[178:181]
	s_and_b64 vcc, exec, s[6:7]
	v_mov_b32_e32 v174, v170
	v_mov_b32_e32 v175, v171
	v_mov_b32_e32 v178, v166
	v_mov_b32_e32 v179, v167
	v_mov_b32_e32 v176, v168
	v_mov_b32_e32 v177, v169
	v_mov_b32_e32 v180, v152
	v_mov_b32_e32 v181, v153
	s_cbranch_vccnz .LBB0_301
	v_mul_f32_e32 v165, 0xbfb8aa3b, v170
	v_exp_f32_e32 v165, v165
	v_mul_f32_e32 v174, 0xbfb8aa3b, v168
	v_exp_f32_e32 v174, v174
	v_mul_f32_e32 v176, 0xbfb8aa3b, v169
	v_add_f32_e32 v165, 1.0, v165
	v_exp_f32_e32 v177, v176
	v_add_f32_e32 v175, 1.0, v174
	v_rcp_f32_e32 v174, v165
	v_mul_f32_e32 v165, 0xbfb8aa3b, v171
	v_exp_f32_e32 v165, v165
	v_rcp_f32_e32 v176, v175
	v_mul_f32_e32 v180, 0xbfb8aa3b, v153
	v_exp_f32_e32 v181, v180
	v_add_f32_e32 v165, 1.0, v165
	v_rcp_f32_e32 v175, v165
	v_add_f32_e32 v165, 1.0, v177
	v_mul_f32_e32 v177, 0xbfb8aa3b, v166
	v_exp_f32_e32 v178, v177
	v_mul_f32_e32 v177, 0xbfb8aa3b, v152
	v_exp_f32_e32 v179, v177
	v_rcp_f32_e32 v177, v165
	v_add_f32_e32 v165, 1.0, v178
	v_rcp_f32_e32 v178, v165
	v_add_f32_e32 v165, 1.0, v179
	v_mul_f32_e32 v179, 0xbfb8aa3b, v167
	v_exp_f32_e32 v179, v179
	v_rcp_f32_e32 v180, v165
	v_pk_mul_f32 v[174:175], v[170:171], v[174:175]
	v_pk_mul_f32 v[176:177], v[168:169], v[176:177]
	v_add_f32_e32 v165, 1.0, v179
	v_rcp_f32_e32 v179, v165
	v_add_f32_e32 v165, 1.0, v181
	v_rcp_f32_e32 v181, v165
	v_pk_mul_f32 v[178:179], v[166:167], v[178:179]
	v_pk_mul_f32 v[180:181], v[152:153], v[180:181]
.LBB0_301:
	s_and_b64 vcc, exec, s[8:9]
	v_cvt_pk_bf16_f32 v174, v174, v175
	v_cvt_pk_bf16_f32 v175, v178, v179
	v_cvt_pk_bf16_f32 v176, v176, v177
	v_cvt_pk_bf16_f32 v177, v180, v181
	ds_write_b128 v234, v[174:177] offset:64
	ds_bpermute_b32 v248, v240, v172
	ds_bpermute_b32 v249, v240, v173
	ds_bpermute_b32 v250, v241, v172
	ds_bpermute_b32 v251, v241, v173
	ds_read_b128 v[226:229], v235
	ds_read_b128 v[230:233], v235 offset:1152
	s_waitcnt lgkmcnt(0)
	v_lshl_add_u64 v[248:249], v[248:249], 0, v[252:253]
	v_lshl_add_u64 v[250:251], v[250:251], 0, v[252:253]
	global_store_dwordx4 v[248:249], v[226:229], off
	global_store_dwordx4 v[250:251], v[230:233], off
	s_cbranch_vccnz .LBB0_305
	v_mul_f32_e32 v163, v163, v163
	v_mul_f32_e32 v159, v159, v159
	v_fmac_f32_e32 v163, v162, v162
	v_fmac_f32_e32 v159, v158, v158
	v_mul_f32_e32 v157, v157, v157
	v_add_f32_e32 v158, v163, v159
	v_fmac_f32_e32 v157, v156, v156
	v_mul_f32_e32 v155, v155, v155
	v_add_f32_e32 v156, v157, v158
	v_fmac_f32_e32 v155, v154, v154
	v_add_f32_e32 v154, v155, v156
	v_mul_f32_e32 v155, v171, v171
	v_mul_f32_e32 v156, v167, v167
	v_fmac_f32_e32 v155, v170, v170
	v_fmac_f32_e32 v156, v166, v166
	v_add_f32_e32 v155, v155, v156
	v_mul_f32_e32 v156, v169, v169
	v_fmac_f32_e32 v156, v168, v168
	v_mul_f32_e32 v153, v153, v153
	v_add_f32_e32 v155, v156, v155
	v_fmac_f32_e32 v153, v152, v152
	v_add_f32_e32 v152, v153, v155
	v_add_f32_e32 v152, v154, v152
	v_and_b32_e32 v154, 64, v192
	v_xor_b32_e32 v153, 16, v192
	v_add_u32_e32 v154, 64, v154
	v_cmp_lt_i32_e32 vcc, v153, v154
	s_nop 1
	v_cndmask_b32_e32 v153, v192, v153, vcc
	v_lshlrev_b32_e32 v153, 2, v153
	ds_bpermute_b32 v153, v153, v152
	s_waitcnt lgkmcnt(0)
	v_add_f32_e32 v152, v152, v153
	v_xor_b32_e32 v153, 32, v192
	v_cmp_lt_i32_e32 vcc, v153, v154
	s_nop 1
	v_cndmask_b32_e32 v153, v192, v153, vcc
	v_lshlrev_b32_e32 v153, 2, v153
	ds_bpermute_b32 v153, v153, v152
	s_and_saveexec_b64 s[2:3], s[10:11]
	s_cbranch_execz .LBB0_304
	s_waitcnt lgkmcnt(0)
	v_add_f32_e32 v154, v152, v153
	v_mul_lo_u32 v155, s1, v164
	v_mul_lo_u32 v151, s0, v151
	v_mad_u64_u32 v[152:153], s[0:1], s0, v164, 0
	v_add3_u32 v153, v153, v151, v155
	v_lshl_add_u64 v[152:153], v[152:153], 2, s[58:59]
	global_store_dword v[152:153], v154, off
